# D3 state wave: preload GL decay table into VGPR lanes, v_readlane per step instead of per-step global load
# speedup vs baseline: 1.0092x; 1.0092x over previous
; #define D3_BAR() do { asm volatile("s_waitcnt lgkmcnt(0)" ::: "memory"); __builtin_amdgcn_s_barrier(); asm volatile("" ::: "memory"); } while (0)
; DI void d3_block(const Params& P, int bh, int vs, LAS unsigned char* lds, int wave, int lane, int tid) {
;     ...
;         f32x16 S[4]; bf16x8 Sb[8];
; #pragma unroll
;         for (int j = 0; j < 4; ++j)
; #pragma unroll
;             for (int i = 0; i < 16; ++i) S[j][i] = 0.f;
; #pragma unroll
;         for (int G = 0; G < 8; ++G) { Sb[G] = (bf16x8){0, 0, 0, 0, 0, 0, 0, 0}; exSb[G * 64] = Sb[G]; }
;         if (lane == 0) *vflag = 0u;
;         D3_BAR();
;         float gl = GL[0];
;     ...
;             const float gl_next = GL[(n + 1) & 127];
.LBB0_367:
	s_or_b64 exec, exec, s[0:1]
	v_readlane_b32 s0, v254, 13
	v_readlane_b32 s4, v254, 56
	v_readlane_b32 s1, v254, 14
	v_readlane_b32 s5, v254, 57
	s_add_u32 s4, s4, s0
	s_addc_u32 s5, s5, s1
	s_waitcnt lgkmcnt(0)
	s_barrier
	v_mov_b32_e32 v0, 0x2a800000
	s_nop 0
	global_load_dword v96, v0, s[4:5]
	s_add_u32 s0, s4, 0x2a800000
	v_mov_b32_e32 v0, 0
	s_addc_u32 s1, s5, 0
	v_lshlrev_b32_e32 v212, 2, v240
	s_nop 0
	global_load_dword v213, v212, s[0:1]
	global_load_dword v214, v212, s[0:1] offset:256
	v_lshlrev_b32_e32 v168, 5, v240
	s_mov_b32 s8, 0
	v_sub_u32_e32 v169, 0, v64
	v_mov_b32_e32 v98, 0
	v_mov_b32_e32 v99, 0
	v_mov_b32_e32 v100, 0
	v_mov_b32_e32 v101, 0
	v_mov_b32_e32 v102, 0
	v_mov_b32_e32 v103, 0
	v_mov_b32_e32 v104, 0
	v_mov_b32_e32 v105, 0
	v_mov_b32_e32 v106, 0
	v_mov_b32_e32 v107, 0
	v_mov_b32_e32 v108, 0
	v_mov_b32_e32 v109, 0
	v_mov_b32_e32 v110, 0
	v_mov_b32_e32 v111, 0
	v_mov_b32_e32 v112, 0
	v_mov_b32_e32 v113, 0
	v_mov_b32_e32 v114, 0
	v_mov_b32_e32 v115, 0
	v_mov_b32_e32 v116, 0
	v_mov_b32_e32 v117, 0
	v_mov_b32_e32 v118, 0
	v_mov_b32_e32 v119, 0
	v_mov_b32_e32 v120, 0
	v_mov_b32_e32 v121, 0
	v_mov_b32_e32 v122, 0
	v_mov_b32_e32 v123, 0
	v_mov_b32_e32 v124, 0
	v_mov_b32_e32 v125, 0
	v_mov_b32_e32 v126, 0
	v_mov_b32_e32 v127, 0
	v_mov_b32_e32 v128, 0
	v_mov_b32_e32 v129, 0
	v_mov_b32_e32 v1, v0
	v_mov_b32_e32 v2, v0
	v_mov_b32_e32 v3, v0
	v_mov_b32_e32 v4, v0
	v_mov_b32_e32 v5, v0
	v_mov_b32_e32 v6, v0
	v_mov_b32_e32 v7, v0
	v_mov_b32_e32 v8, v0
	v_mov_b32_e32 v9, v0
	v_mov_b32_e32 v10, v0
	v_mov_b32_e32 v11, v0
	v_mov_b32_e32 v12, v0
	v_mov_b32_e32 v13, v0
	v_mov_b32_e32 v14, v0
	v_mov_b32_e32 v15, v0
	v_mov_b32_e32 v16, v0
	v_mov_b32_e32 v17, v0
	v_mov_b32_e32 v18, v0
	v_mov_b32_e32 v19, v0
	v_mov_b32_e32 v20, v0
	v_mov_b32_e32 v21, v0
	v_mov_b32_e32 v22, v0
	v_mov_b32_e32 v23, v0
	v_mov_b32_e32 v24, v0
	v_mov_b32_e32 v25, v0
	v_mov_b32_e32 v26, v0
	v_mov_b32_e32 v27, v0
	v_mov_b32_e32 v28, v0
	v_mov_b32_e32 v29, v0
	v_mov_b32_e32 v30, v0
	v_mov_b32_e32 v31, v0
	v_mov_b32_e32 v32, v0
	v_mov_b32_e32 v33, v0
	v_mov_b32_e32 v34, v0
	v_mov_b32_e32 v35, v0
	v_mov_b32_e32 v36, v0
	v_mov_b32_e32 v37, v0
	v_mov_b32_e32 v38, v0
	v_mov_b32_e32 v39, v0
	v_mov_b32_e32 v40, v0
	v_mov_b32_e32 v41, v0
	v_mov_b32_e32 v42, v0
	v_mov_b32_e32 v43, v0
	v_mov_b32_e32 v44, v0
	v_mov_b32_e32 v45, v0
	v_mov_b32_e32 v46, v0
	v_mov_b32_e32 v47, v0
	v_mov_b32_e32 v48, v0
	v_mov_b32_e32 v49, v0
	v_mov_b32_e32 v50, v0
	v_mov_b32_e32 v51, v0
	v_mov_b32_e32 v52, v0
	v_mov_b32_e32 v53, v0
	v_mov_b32_e32 v54, v0
	v_mov_b32_e32 v55, v0
	v_mov_b32_e32 v56, v0
	v_mov_b32_e32 v57, v0
	v_mov_b32_e32 v58, v0
	v_mov_b32_e32 v59, v0
	v_mov_b32_e32 v60, v0
	v_mov_b32_e32 v61, v0
	v_mov_b32_e32 v62, v0
	v_mov_b32_e32 v63, v0
	s_waitcnt vmcnt(0)
	s_branch .LBB0_369

; #define LAS __attribute__((address_space(3)))
; #define MFMA32(a, b, c) __builtin_amdgcn_mfma_f32_32x32x16_bf16((a), (b), (c), 0, 0, 0)
; DI float bflo(unsigned u) { return __uint_as_float(u << 16); }
; DI float bfhi(unsigned u) { return __uint_as_float(u & 0xffff0000u); }
; DI void d3_block(const Params& P, int bh, int vs, LAS unsigned char* lds, int wave, int lane, int tid) {
;     ...
;         for (int n = 0; n < 128; ++n) {
;             const LAS unsigned char* sb = lds + (n & 1) * D3_SLOT;
;             const LAS bf16x8* fNW = (const LAS bf16x8*)sb + lane; const LAS bf16x8* fKD = (const LAS bf16x8*)(sb + 40960) + lane;
;             const LAS u32x4* fU = (const LAS u32x4*)(sb + 57344) + lane * 2;
;             const float gl_next = GL[(n + 1) & 127];
;             bf16x8 fw[16];
; #pragma unroll
;             for (int q = 0; q < 16; ++q) fw[q] = fNW[q * 64];
;             f32x16 vt[2];
; #pragma unroll
;             for (int t = 0; t < 2; ++t) { const u32x4 a = fU[t * 128], b2 = fU[t * 128 + 1];
;                 vt[t][0] = bflo(a.x); vt[t][1] = bfhi(a.x); vt[t][2] = bflo(a.y); vt[t][3] = bfhi(a.y); vt[t][4] = bflo(a.z); vt[t][5] = bfhi(a.z); vt[t][6] = bflo(a.w); vt[t][7] = bfhi(a.w);
;                 vt[t][8] = bflo(b2.x); vt[t][9] = bfhi(b2.x); vt[t][10] = bflo(b2.y); vt[t][11] = bfhi(b2.y); vt[t][12] = bflo(b2.z); vt[t][13] = bfhi(b2.z); vt[t][14] = bflo(b2.w); vt[t][15] = bfhi(b2.w); }
;             __builtin_amdgcn_sched_barrier(0);
; #pragma unroll
;             for (int G = 0; G < 8; ++G) {
;                 vt[0] = MFMA32(fw[G], Sb[G], vt[0]); vt[1] = MFMA32(fw[8 + G], Sb[G], vt[1]);
;                 if (G < 4) {
; #pragma unroll
;                     for (int i = 0; i < 16; ++i) S[G][i] *= gl; } }
;             __builtin_amdgcn_sched_barrier(0);
;             bf16x8 fk[16];
; #pragma unroll
;             for (int q = 0; q < 16; ++q) fk[q] = fKD[q * 64];
;             __builtin_amdgcn_sched_barrier(0);
;             bf16x8 Vb[4];
;             Vb[0] = pack8(vt[0], 0); Vb[1] = pack8(vt[0], 1); Vb[2] = pack8(vt[1], 0); Vb[3] = pack8(vt[1], 1);
; #pragma unroll
;             for (int G = 0; G < 4; ++G) exVb[G * 64] = Vb[G];
;             asm volatile("s_waitcnt lgkmcnt(0)" ::: "memory");
;             if (lane == 0) *vflag = (unsigned)(n + 1);
.LBB0_369:
	s_bitcmp1_b32 s8, 0
	s_cselect_b32 s4, 0xf000, 0
	s_add_i32 s8, s8, 1
	s_and_b32 s5, s8, 63
	s_bitcmp1_b32 s8, 6
	s_nop 3
	v_readlane_b32 s9, v213, s5
	s_cbranch_scc0 .Ld3_gl_lo
	v_readlane_b32 s9, v214, s5
.Ld3_gl_lo:
	s_nop 2
	v_mov_b32_e32 v170, s9
	s_add_i32 s4, s4, 0
	v_lshl_add_u32 v64, v240, 4, s4
	ds_read_b128 v[130:133], v64
	ds_read_b128 v[134:137], v64 offset:1024
	ds_read_b128 v[138:141], v64 offset:2048
	ds_read_b128 v[142:145], v64 offset:3072
	ds_read_b128 v[146:149], v64 offset:4096
	ds_read_b128 v[150:153], v64 offset:5120
	ds_read_b128 v[154:157], v64 offset:6144
	ds_read_b128 v[158:161], v64 offset:7168
	ds_read_b128 v[162:165], v64 offset:8192
	ds_read_b128 v[172:175], v64 offset:9216
	ds_read_b128 v[176:179], v64 offset:10240
	ds_read_b128 v[184:187], v64 offset:11264
	v_add_u32_e32 v171, s4, v168
	ds_read_b128 v[68:71], v171 offset:57344
	ds_read_b128 v[196:199], v64 offset:12288
	ds_read_b128 v[200:203], v64 offset:13312
	ds_read_b128 v[204:207], v64 offset:14336
	ds_read_b128 v[208:211], v64 offset:15360
	ds_read_b128 v[76:79], v171 offset:57360
	ds_read_b128 v[84:87], v171 offset:59392
	ds_read_b128 v[92:95], v171 offset:59408
	s_waitcnt lgkmcnt(0)
	v_lshlrev_b32_e32 v64, 16, v68
	v_and_b32_e32 v65, 0xffff0000, v68
	v_lshlrev_b32_e32 v66, 16, v69
	v_and_b32_e32 v67, 0xffff0000, v69
	v_lshlrev_b32_e32 v68, 16, v70
	v_and_b32_e32 v69, 0xffff0000, v70
	v_lshlrev_b32_e32 v70, 16, v71
	v_and_b32_e32 v71, 0xffff0000, v71
	v_lshlrev_b32_e32 v72, 16, v76
	v_and_b32_e32 v73, 0xffff0000, v76
	v_lshlrev_b32_e32 v74, 16, v77
	v_and_b32_e32 v75, 0xffff0000, v77
	v_lshlrev_b32_e32 v76, 16, v78
	v_and_b32_e32 v77, 0xffff0000, v78
	v_lshlrev_b32_e32 v78, 16, v79
	v_and_b32_e32 v79, 0xffff0000, v79
	v_lshlrev_b32_e32 v80, 16, v84
	v_and_b32_e32 v81, 0xffff0000, v84
	v_lshlrev_b32_e32 v82, 16, v85
	v_and_b32_e32 v83, 0xffff0000, v85
	v_lshlrev_b32_e32 v84, 16, v86
	v_and_b32_e32 v85, 0xffff0000, v86
	v_lshlrev_b32_e32 v86, 16, v87
	v_and_b32_e32 v87, 0xffff0000, v87
	v_lshlrev_b32_e32 v88, 16, v92
	v_and_b32_e32 v89, 0xffff0000, v92
	v_lshlrev_b32_e32 v90, 16, v93
	v_and_b32_e32 v91, 0xffff0000, v93
	v_lshlrev_b32_e32 v92, 16, v94
	v_and_b32_e32 v93, 0xffff0000, v94
	v_lshlrev_b32_e32 v94, 16, v95
	v_and_b32_e32 v95, 0xffff0000, v95
	v_mfma_f32_32x32x16_bf16 v[64:79], v[130:133], v[98:101], v[64:79]
	s_nop 0
	v_mfma_f32_32x32x16_bf16 v[80:95], v[162:165], v[98:101], v[80:95]
	v_mfma_f32_32x32x16_bf16 v[64:79], v[134:137], v[102:105], v[64:79]
	v_mfma_f32_32x32x16_bf16 v[80:95], v[172:175], v[102:105], v[80:95]
	v_mfma_f32_32x32x16_bf16 v[64:79], v[138:141], v[106:109], v[64:79]
	v_mfma_f32_32x32x16_bf16 v[80:95], v[176:179], v[106:109], v[80:95]
	v_mfma_f32_32x32x16_bf16 v[64:79], v[142:145], v[110:113], v[64:79]
	v_mfma_f32_32x32x16_bf16 v[80:95], v[184:187], v[110:113], v[80:95]
	v_add_u32_e32 v110, v171, v169
	v_mfma_f32_32x32x16_bf16 v[64:79], v[146:149], v[114:117], v[64:79]
	v_mfma_f32_32x32x16_bf16 v[80:95], v[196:199], v[114:117], v[80:95]
	v_mfma_f32_32x32x16_bf16 v[64:79], v[150:153], v[118:121], v[64:79]
	v_mfma_f32_32x32x16_bf16 v[80:95], v[200:203], v[118:121], v[80:95]
	v_mfma_f32_32x32x16_bf16 v[64:79], v[154:157], v[122:125], v[64:79]
	v_mfma_f32_32x32x16_bf16 v[80:95], v[204:207], v[122:125], v[80:95]
	v_mfma_f32_32x32x16_bf16 v[64:79], v[158:161], v[126:129], v[64:79]
	v_mfma_f32_32x32x16_bf16 v[80:95], v[208:211], v[126:129], v[80:95]
	ds_read_b128 v[162:165], v110 offset:40960
	ds_read_b128 v[130:133], v110 offset:41984
	ds_read_b128 v[114:117], v110 offset:43008
	ds_read_b128 v[98:101], v110 offset:44032
	ds_read_b128 v[158:161], v110 offset:45056
	ds_read_b128 v[134:137], v110 offset:46080
	ds_read_b128 v[118:121], v110 offset:47104
	ds_read_b128 v[102:105], v110 offset:48128
	ds_read_b128 v[150:153], v110 offset:49152
	ds_read_b128 v[138:141], v110 offset:50176
	ds_read_b128 v[122:125], v110 offset:51200
	ds_read_b128 v[106:109], v110 offset:52224
	ds_read_b128 v[146:149], v110 offset:53248
	ds_read_b128 v[142:145], v110 offset:54272
	ds_read_b128 v[126:129], v110 offset:55296
	ds_read_b128 v[110:113], v110 offset:56320
	v_cvt_pk_bf16_f32 v154, v64, v65
	v_cvt_pk_bf16_f32 v155, v66, v67
	v_cvt_pk_bf16_f32 v156, v68, v69
	v_cvt_pk_bf16_f32 v157, v70, v71
	v_cvt_pk_bf16_f32 v72, v72, v73
	v_cvt_pk_bf16_f32 v73, v74, v75
	v_cvt_pk_bf16_f32 v74, v76, v77
	v_cvt_pk_bf16_f32 v75, v78, v79
	v_cvt_pk_bf16_f32 v68, v80, v81
	v_cvt_pk_bf16_f32 v69, v82, v83
	v_cvt_pk_bf16_f32 v70, v84, v85
	v_cvt_pk_bf16_f32 v71, v86, v87
	v_cvt_pk_bf16_f32 v64, v88, v89
	v_cvt_pk_bf16_f32 v65, v90, v91
	v_cvt_pk_bf16_f32 v66, v92, v93
	v_cvt_pk_bf16_f32 v67, v94, v95
	ds_write_b128 v167, v[154:157]
	ds_write_b128 v167, v[72:75] offset:1024
	ds_write_b128 v167, v[68:71] offset:2048
	ds_write_b128 v167, v[64:67] offset:3072
	s_waitcnt lgkmcnt(0)
	s_and_saveexec_b64 s[4:5], vcc
	s_cbranch_execz .LBB0_368
	v_readlane_b32 s9, v254, 21
	v_mov_b32_e32 v77, s8
	s_nop 0
	v_mov_b32_e32 v76, s9
	ds_write_b32 v76, v77
	s_branch .LBB0_368
